# speedup vs baseline: 1.0274x; 1.0084x over previous
; DI void phase_cp(const Params& p, int l, char* smem) {
;     ...
;     const int total = 128 + 256 * 6 + 256 * 8;
;     for (int id = blockIdx.x; id < total; id += gridDim.x) {
;         f32x16 acc[2][2];
;         if (id < 128) {
.LBB0_1471:
	s_load_dword s0, s[96:97], 0x10
	s_load_dword s8, s[96:97], 0x0
	s_waitcnt lgkmcnt(0)
	s_lshr_b32 s0, s0, 16
	s_cmp_lg_u32 s0, 0
	s_cselect_b64 s[0:1], -1, 0
	s_cmp_lg_u64 s[0:1], 0
	s_addc_u32 s8, s8, 0
	v_readlane_b32 s0, v247, 52
	s_cmpk_lt_u32 s0, 0x80
	s_cbranch_scc1 .LBB0_1549
	s_addk_i32 s8, 0xff80
	s_add_i32 s72, s72, s8
	s_cmpk_gt_i32 s72, 0xe7f
	s_cbranch_scc1 .LBB0_1549
